# adds: MLA attention block epilogue transposes the wave's O tile through dead K-tile LDS and stores 8 x dwordx4 full 128B row segments instead of 64 ds_swizzle + 64 dword stores
# speedup vs baseline: 1.0058x; 1.0047x over previous
.LBB0_163:
	s_and_saveexec_b64 s[36:37], s[38:39]
	ds_write_b32 v205, v80
	s_or_b64 exec, exec, s[36:37]
	s_waitcnt lgkmcnt(0)
	ds_read_b128 v[76:79], v203
	ds_read_b128 v[72:75], v203 offset:32
	ds_read_b128 v[68:71], v203 offset:64
	ds_read_b128 v[64:67], v203 offset:96
	s_lshl_b64 s[18:19], s[18:19], 11
	s_add_u32 s2, s78, s18
	s_addc_u32 s8, s79, s19
	s_add_u32 s2, s2, s28
	s_addc_u32 s8, s8, s29
	s_ashr_i32 s57, s56, 31
	s_lshl_b64 s[18:19], s[56:57], 11
	s_add_u32 s18, s2, s18
	s_addc_u32 s19, s8, s19
	s_add_u32 s18, s18, 0x2a800000
	s_addc_u32 s19, s19, 0
	v_readlane_b32 s2, v254, 50
	v_lshrrev_b32_e32 v82, 3, v252
	v_and_b32_e32 v83, 7, v252
	s_mul_i32 s2, s2, 0x1800
	s_add_i32 s2, s2, 0xc000
	v_lshlrev_b32_e32 v84, 11, v82
	v_lshl_or_b32 v84, v83, 4, v84
	v_add_u32_e32 v85, 0x4000, v84
	v_add_u32_e32 v86, 0x8000, v84
	v_add_u32_e32 v87, 0xc000, v84
	v_mul_u32_u24_e32 v88, 144, v82
	v_lshl_add_u32 v88, v83, 4, v88
	v_add_u32_e32 v88, s2, v88
	v_lshrrev_b32_e32 v82, 5, v252
	v_and_b32_e32 v83, 31, v252
	v_mul_u32_u24_e32 v89, 576, v82
	v_lshl_add_u32 v89, v83, 1, v89
	v_add_u32_e32 v89, s2, v89
	s_waitcnt lgkmcnt(0)
	v_rcp_f32_e32 v64, v64
	v_rcp_f32_e32 v65, v65
	v_rcp_f32_e32 v66, v66
	v_rcp_f32_e32 v67, v67
	v_rcp_f32_e32 v68, v68
	v_rcp_f32_e32 v69, v69
	v_rcp_f32_e32 v70, v70
	v_rcp_f32_e32 v71, v71
	v_rcp_f32_e32 v72, v72
	v_rcp_f32_e32 v73, v73
	v_rcp_f32_e32 v74, v74
	v_rcp_f32_e32 v75, v75
	v_rcp_f32_e32 v76, v76
	v_rcp_f32_e32 v77, v77
	v_rcp_f32_e32 v78, v78
	v_rcp_f32_e32 v79, v79
	s_nop 0
	v_pk_mul_f32 v[32:33], v[32:33], v[76:77]
	v_pk_mul_f32 v[34:35], v[34:35], v[78:79]
	v_pk_mul_f32 v[36:37], v[36:37], v[72:73]
	v_pk_mul_f32 v[38:39], v[38:39], v[74:75]
	v_pk_mul_f32 v[40:41], v[40:41], v[68:69]
	v_pk_mul_f32 v[42:43], v[42:43], v[70:71]
	v_pk_mul_f32 v[44:45], v[44:45], v[64:65]
	v_pk_mul_f32 v[46:47], v[46:47], v[66:67]
	v_pk_mul_f32 v[48:49], v[48:49], v[76:77]
	v_pk_mul_f32 v[50:51], v[50:51], v[78:79]
	v_pk_mul_f32 v[52:53], v[52:53], v[72:73]
	v_pk_mul_f32 v[54:55], v[54:55], v[74:75]
	v_pk_mul_f32 v[56:57], v[56:57], v[68:69]
	v_pk_mul_f32 v[58:59], v[58:59], v[70:71]
	v_pk_mul_f32 v[60:61], v[60:61], v[64:65]
	v_pk_mul_f32 v[62:63], v[62:63], v[66:67]
	v_pk_mul_f32 v[16:17], v[16:17], v[76:77]
	v_pk_mul_f32 v[18:19], v[18:19], v[78:79]
	v_pk_mul_f32 v[20:21], v[20:21], v[72:73]
	v_pk_mul_f32 v[22:23], v[22:23], v[74:75]
	v_pk_mul_f32 v[24:25], v[24:25], v[68:69]
	v_pk_mul_f32 v[26:27], v[26:27], v[70:71]
	v_pk_mul_f32 v[28:29], v[28:29], v[64:65]
	v_pk_mul_f32 v[30:31], v[30:31], v[66:67]
	v_pk_mul_f32 v[0:1], v[0:1], v[76:77]
	v_pk_mul_f32 v[2:3], v[2:3], v[78:79]
	v_pk_mul_f32 v[4:5], v[4:5], v[72:73]
	v_pk_mul_f32 v[6:7], v[6:7], v[74:75]
	v_pk_mul_f32 v[8:9], v[8:9], v[68:69]
	v_pk_mul_f32 v[10:11], v[10:11], v[70:71]
	v_pk_mul_f32 v[12:13], v[12:13], v[64:65]
	v_pk_mul_f32 v[14:15], v[14:15], v[66:67]
	v_cvt_pk_bf16_f32 v32, v32, v33
	v_cvt_pk_bf16_f32 v34, v34, v35
	v_cvt_pk_bf16_f32 v36, v36, v37
	v_cvt_pk_bf16_f32 v38, v38, v39
	v_cvt_pk_bf16_f32 v40, v40, v41
	v_cvt_pk_bf16_f32 v42, v42, v43
	v_cvt_pk_bf16_f32 v44, v44, v45
	v_cvt_pk_bf16_f32 v46, v46, v47
	v_cvt_pk_bf16_f32 v48, v48, v49
	v_cvt_pk_bf16_f32 v50, v50, v51
	v_cvt_pk_bf16_f32 v52, v52, v53
	v_cvt_pk_bf16_f32 v54, v54, v55
	v_cvt_pk_bf16_f32 v56, v56, v57
	v_cvt_pk_bf16_f32 v58, v58, v59
	v_cvt_pk_bf16_f32 v60, v60, v61
	v_cvt_pk_bf16_f32 v62, v62, v63
	v_cvt_pk_bf16_f32 v16, v16, v17
	v_cvt_pk_bf16_f32 v18, v18, v19
	v_cvt_pk_bf16_f32 v20, v20, v21
	v_cvt_pk_bf16_f32 v22, v22, v23
	v_cvt_pk_bf16_f32 v24, v24, v25
	v_cvt_pk_bf16_f32 v26, v26, v27
	v_cvt_pk_bf16_f32 v28, v28, v29
	v_cvt_pk_bf16_f32 v30, v30, v31
	v_cvt_pk_bf16_f32 v0, v0, v1
	v_cvt_pk_bf16_f32 v2, v2, v3
	v_cvt_pk_bf16_f32 v4, v4, v5
	v_cvt_pk_bf16_f32 v6, v6, v7
	v_cvt_pk_bf16_f32 v8, v8, v9
	v_cvt_pk_bf16_f32 v10, v10, v11
	v_cvt_pk_bf16_f32 v12, v12, v13
	v_cvt_pk_bf16_f32 v14, v14, v15
	ds_write_b16 v89, v32 offset:0
	ds_write_b16_d16_hi v89, v32 offset:144
	ds_write_b16 v89, v34 offset:288
	ds_write_b16_d16_hi v89, v34 offset:432
	ds_write_b16 v89, v36 offset:1152
	ds_write_b16_d16_hi v89, v36 offset:1296
	ds_write_b16 v89, v38 offset:1440
	ds_write_b16_d16_hi v89, v38 offset:1584
	ds_write_b16 v89, v40 offset:2304
	ds_write_b16_d16_hi v89, v40 offset:2448
	ds_write_b16 v89, v42 offset:2592
	ds_write_b16_d16_hi v89, v42 offset:2736
	ds_write_b16 v89, v44 offset:3456
	ds_write_b16_d16_hi v89, v44 offset:3600
	ds_write_b16 v89, v46 offset:3744
	ds_write_b16_d16_hi v89, v46 offset:3888
	ds_write_b16 v89, v48 offset:64
	ds_write_b16_d16_hi v89, v48 offset:208
	ds_write_b16 v89, v50 offset:352
	ds_write_b16_d16_hi v89, v50 offset:496
	ds_write_b16 v89, v52 offset:1216
	ds_write_b16_d16_hi v89, v52 offset:1360
	ds_write_b16 v89, v54 offset:1504
	ds_write_b16_d16_hi v89, v54 offset:1648
	ds_write_b16 v89, v56 offset:2368
	ds_write_b16_d16_hi v89, v56 offset:2512
	ds_write_b16 v89, v58 offset:2656
	ds_write_b16_d16_hi v89, v58 offset:2800
	ds_write_b16 v89, v60 offset:3520
	ds_write_b16_d16_hi v89, v60 offset:3664
	ds_write_b16 v89, v62 offset:3808
	ds_write_b16_d16_hi v89, v62 offset:3952
	ds_read_b128 v[64:67], v88 offset:0
	ds_read_b128 v[68:71], v88 offset:1152
	ds_read_b128 v[72:75], v88 offset:2304
	ds_read_b128 v[76:79], v88 offset:3456
	s_waitcnt lgkmcnt(3)
	global_store_dwordx4 v84, v[64:67], s[18:19]
	s_waitcnt lgkmcnt(2)
	global_store_dwordx4 v85, v[68:71], s[18:19]
	s_waitcnt lgkmcnt(1)
	global_store_dwordx4 v86, v[72:75], s[18:19]
	s_waitcnt lgkmcnt(0)
	global_store_dwordx4 v87, v[76:79], s[18:19]
	ds_write_b16 v89, v16 offset:0
	ds_write_b16_d16_hi v89, v16 offset:144
	ds_write_b16 v89, v18 offset:288
	ds_write_b16_d16_hi v89, v18 offset:432
	ds_write_b16 v89, v20 offset:1152
	ds_write_b16_d16_hi v89, v20 offset:1296
	ds_write_b16 v89, v22 offset:1440
	ds_write_b16_d16_hi v89, v22 offset:1584
	ds_write_b16 v89, v24 offset:2304
	ds_write_b16_d16_hi v89, v24 offset:2448
	ds_write_b16 v89, v26 offset:2592
	ds_write_b16_d16_hi v89, v26 offset:2736
	ds_write_b16 v89, v28 offset:3456
	ds_write_b16_d16_hi v89, v28 offset:3600
	ds_write_b16 v89, v30 offset:3744
	ds_write_b16_d16_hi v89, v30 offset:3888
	ds_write_b16 v89, v0 offset:64
	ds_write_b16_d16_hi v89, v0 offset:208
	ds_write_b16 v89, v2 offset:352
	ds_write_b16_d16_hi v89, v2 offset:496
	ds_write_b16 v89, v4 offset:1216
	ds_write_b16_d16_hi v89, v4 offset:1360
	ds_write_b16 v89, v6 offset:1504
	ds_write_b16_d16_hi v89, v6 offset:1648
	ds_write_b16 v89, v8 offset:2368
	ds_write_b16_d16_hi v89, v8 offset:2512
	ds_write_b16 v89, v10 offset:2656
	ds_write_b16_d16_hi v89, v10 offset:2800
	ds_write_b16 v89, v12 offset:3520
	ds_write_b16_d16_hi v89, v12 offset:3664
	ds_write_b16 v89, v14 offset:3808
	ds_write_b16_d16_hi v89, v14 offset:3952
	ds_read_b128 v[32:35], v88 offset:0
	ds_read_b128 v[36:39], v88 offset:1152
	ds_read_b128 v[40:43], v88 offset:2304
	ds_read_b128 v[44:47], v88 offset:3456
	s_waitcnt lgkmcnt(3)
	global_store_dwordx4 v84, v[32:35], s[18:19] offset:128
	s_waitcnt lgkmcnt(2)
	global_store_dwordx4 v85, v[36:39], s[18:19] offset:128
	s_waitcnt lgkmcnt(1)
	global_store_dwordx4 v86, v[40:43], s[18:19] offset:128
	s_waitcnt lgkmcnt(0)
	global_store_dwordx4 v87, v[44:47], s[18:19] offset:128
	s_branch .LBB0_144
